# q-up/kv-up MFMAs paired too; MLA QK segments 8-11 issued as two 4-long accumulator chains
# baseline (speedup 1.0000x reference)
; template <int MODE, int VARI>
; __device__ __forceinline__ void attn_unit(LAS unsigned char* lds, const int tid, const AttnP& a, float c2, float lam, const float* subln, float outscale, float fox_u, const bool fast) {
;     ...
;       unsigned voff[2], koff[KW / 64], kstp[KW / 64], boff = 0; int vt = t_lo, kt = t_lo;
;       { int tt_ = tid; asm volatile("" : "+v"(tt_)); const int ln_ = tt_ & 63;
; #pragma unroll
;         for (int i_ = 0; i_ < 2; ++i_) { const int ch_ = wid + 8 * i_, b_ = ch_ * 1024 + ln_ * 16, sub_ = b_ >> 9, wi_ = (b_ & 511) >> 1;
;             const int kk_ = (sub_ >> 2) * 8 + (wi_ >> 5), c_ = (sub_ & 3) * 32 + (wi_ & 31), k_ = (kk_ & ~0xC) | ((kk_ & 4) << 1) | ((kk_ & 8) >> 1);
;             voff[i_] = (unsigned)(((t_lo * 64 + k_) * a.vpitch + c_) * 2); }
; #pragma unroll
;         for (int i_ = 0; i_ < KW / 64; ++i_) { const int ch_ = wid + 8 * i_, b_ = ch_ * 1024 + ln_ * 16, krow_ = b_ / (KW * 2), cs_ = (b_ % (KW * 2)) >> 4;
;             const int kcc_ = cs_ ^ (kswz<KW>(krow_) >> 4);
;             if (MODE == 2 && kcc_ >= 8) { koff[i_] = (unsigned)((const char*)a.K1 - (const char*)a.K0) + (unsigned)(((t_lo * 64 + krow_) * a.k1pitch + (kcc_ - 8) * 8) * 2); kstp[i_] = (unsigned)(64 * a.k1pitch * 2); }
;             else { koff[i_] = (unsigned)(((t_lo * 64 + krow_) * a.k0pitch + kcc_ * 8) * 2); kstp[i_] = (unsigned)(64 * a.k0pitch * 2); } }
;         if (MODE == 1) boff = (unsigned)((t_lo * 64 + ln_) * 32); }
.LBB0_626:
	s_lshl_b32 s2, s9, 14
	s_add_i32 s2, s58, s2
	v_lshl_add_u64 v[2:3], s[60:61], 0, v[0:1]
	v_lshl_add_u64 v[2:3], v[2:3], 0, s[96:97]
	s_mov_b32 m0, s2
	v_mov_b32_e32 v15, v1
	global_load_lds_dwordx4 v[2:3], off
	v_lshl_add_u64 v[2:3], s[60:61], 0, v[14:15]
	v_lshl_add_u64 v[2:3], v[2:3], 0, s[96:97]
	s_add_i32 m0, s2, 0x2000
	s_cmp_lt_u32 s27, s59
	global_load_lds_dwordx4 v[2:3], off
	s_cselect_b64 vcc, -1, 0
	v_add_u32_e32 v2, 0x30000, v0
	v_add_u32_e32 v3, 0x30000, v14
	s_cmp_lg_u64 vcc, 0
	v_cndmask_b32_e32 v14, v14, v3, vcc
	v_cndmask_b32_e32 v0, v0, v2, vcc
	s_addc_u32 s27, s27, 0
	s_mul_i32 s2, s12, 0x6000
	v_add_u32_e32 v15, s2, v236
	v_add_u32_e32 v6, v15, v241
	ds_read_b128 v[2:5], v6
	ds_read_b128 v[6:9], v6 offset:12288
	v_exp_f32_e32 v12, v96
	s_waitcnt lgkmcnt(0)
	v_mfma_f32_32x32x16_bf16 v[112:127], v[2:5], v[144:147], 0
	v_mov_b32_e32 v2, v97
	v_exp_f32_e32 v96, v98
	v_exp_f32_e32 v97, v99
	v_exp_f32_e32 v13, v2
	v_mfma_f32_32x32x16_bf16 v[128:143], v[6:9], v[144:147], 0
	v_add_u32_e32 v2, v15, v242
	ds_read_b128 v[4:7], v2
	ds_read_b128 v[8:11], v2 offset:12288
	v_mov_b32_e32 v2, v100
	v_mov_b32_e32 v3, v101
	v_exp_f32_e32 v98, v2
	v_exp_f32_e32 v99, v3
	v_exp_f32_e32 v100, v102
	v_exp_f32_e32 v101, v103
	v_cvt_pk_bf16_f32 v2, v12, v13
	s_waitcnt lgkmcnt(0)
	v_mfma_f32_32x32x16_bf16 v[112:127], v[4:7], v[148:151], v[112:127]
	v_cvt_pk_bf16_f32 v3, v96, v97
	v_cvt_pk_bf16_f32 v4, v98, v99
	v_cvt_pk_bf16_f32 v5, v100, v101
	s_nop 0
	v_permlane32_swap_b32_e32 v2, v4
	v_permlane32_swap_b32_e32 v3, v5
	v_mfma_f32_32x32x16_bf16 v[128:143], v[8:11], v[148:151], v[128:143]
	v_add_u32_e32 v10, v15, v243
	ds_read_b128 v[6:9], v10
	v_add_f32_e64 v102, v214, v12
	v_add_f32_e64 v103, v215, v13
	ds_read_b128 v[10:13], v10 offset:12288
	v_exp_f32_e32 v104, v104
	v_exp_f32_e32 v105, v105
	s_waitcnt lgkmcnt(0)
	v_mfma_f32_32x32x16_bf16 v[112:127], v[6:9], v[152:155], v[112:127]
	v_add_f32_e64 v6, v96, v102
	v_add_f32_e64 v7, v97, v103
	v_exp_f32_e32 v102, v106
	v_exp_f32_e32 v103, v107
	v_pk_add_f32 v[6:7], v[98:99], v[6:7]
	s_nop 0
	v_pk_add_f32 v[6:7], v[100:101], v[6:7]
	s_nop 0
	v_pk_add_f32 v[100:101], v[104:105], v[6:7]
	v_mfma_f32_32x32x16_bf16 v[128:143], v[10:13], v[152:155], v[128:143]
	v_add_u32_e32 v6, v15, v244
	ds_read_b128 v[8:11], v6
	ds_read_b128 v[96:99], v6 offset:12288
	v_exp_f32_e32 v106, v108
	v_exp_f32_e32 v107, v109
	v_exp_f32_e32 v108, v110
	v_exp_f32_e32 v109, v111
	v_cvt_pk_bf16_f32 v6, v104, v105
	s_waitcnt lgkmcnt(0)
	v_mfma_f32_32x32x16_bf16 v[112:127], v[8:11], v[156:159], v[112:127]
	v_cvt_pk_bf16_f32 v7, v102, v103
	v_cvt_pk_bf16_f32 v8, v106, v107
	v_cvt_pk_bf16_f32 v9, v108, v109
	s_nop 0
	v_permlane32_swap_b32_e32 v6, v8
	v_permlane32_swap_b32_e32 v7, v9
	v_mfma_f32_32x32x16_bf16 v[128:143], v[96:99], v[156:159], v[128:143]
	v_add_u32_e32 v96, v15, v245
	ds_read_b128 v[10:13], v96
	ds_read_b128 v[96:99], v96 offset:12288
	v_exp_f32_e32 v104, v80
	s_waitcnt lgkmcnt(0)
	v_mfma_f32_32x32x16_bf16 v[112:127], v[10:13], v[160:163], v[112:127]
	v_exp_f32_e32 v105, v81
	v_exp_f32_e32 v110, v82
	v_exp_f32_e32 v111, v83
	v_mfma_f32_32x32x16_bf16 v[128:143], v[96:99], v[160:163], v[128:143]
	v_add_u32_e32 v80, v15, v246
	ds_read_b128 v[10:13], v80
	ds_read_b128 v[80:83], v80 offset:12288
	v_exp_f32_e32 v96, v84
	v_exp_f32_e32 v97, v85
	v_exp_f32_e32 v98, v86
	v_exp_f32_e32 v99, v87
	v_cvt_pk_bf16_f32 v192, v104, v105
	v_cvt_pk_bf16_f32 v193, v110, v111
	v_cvt_pk_bf16_f32 v194, v96, v97
	v_cvt_pk_bf16_f32 v195, v98, v99
	s_waitcnt lgkmcnt(0)
	v_mfma_f32_32x32x16_bf16 v[112:127], v[10:13], v[164:167], v[112:127]
	v_permlane32_swap_b32_e32 v192, v194
	v_permlane32_swap_b32_e32 v193, v195
	v_mfma_f32_32x32x16_bf16 v[128:143], v[80:83], v[164:167], v[128:143]
	v_add_u32_e32 v80, v15, v247
	ds_read_b128 v[10:13], v80
	ds_read_b128 v[80:83], v80 offset:12288
	s_waitcnt lgkmcnt(0)
	v_mfma_f32_32x32x16_bf16 v[112:127], v[10:13], v[168:171], v[112:127]
	v_exp_f32_e32 v10, v88
	v_exp_f32_e32 v11, v89
	v_exp_f32_e32 v12, v90
	v_exp_f32_e32 v13, v91
	v_mfma_f32_32x32x16_bf16 v[128:143], v[80:83], v[168:171], v[128:143]
	v_mov_b32_e32 v88, v92
	v_mov_b32_e32 v89, v93
	v_add_f32_e64 v92, v102, v100
	v_add_f32_e64 v93, v103, v101
	v_add_u32_e32 v84, v15, v248
	v_pk_add_f32 v[92:93], v[106:107], v[92:93]
	v_pk_add_f32 v[92:93], v[108:109], v[92:93]
	v_pk_add_f32 v[92:93], v[104:105], v[92:93]
	v_exp_f32_e32 v88, v88
	v_pk_add_f32 v[92:93], v[110:111], v[92:93]
	v_exp_f32_e32 v89, v89
	v_pk_add_f32 v[92:93], v[96:97], v[92:93]
	ds_read_b128 v[80:83], v84
	ds_read_b128 v[84:87], v84 offset:12288
	v_exp_f32_e32 v90, v94
	v_exp_f32_e32 v91, v95
	v_pk_add_f32 v[92:93], v[98:99], v[92:93]
	s_waitcnt lgkmcnt(0)
; #define SBAR() __builtin_amdgcn_sched_barrier(0)
; #define VSET(S, d0) do { constexpr int b_ = (d0) * 512; TRRD(S##l0, b_); TRRD(S##h0, b_ + 2048); TRRD(S##l1, b_ + 4096); TRRD(S##h1, b_ + 6144); \
;         TRRD(S##l2, b_ + 8192); TRRD(S##h2, b_ + 10240); TRRD(S##l3, b_ + 12288); TRRD(S##h3, b_ + 14336); } while (0)
; #define LWAIT(n) do { asm volatile("s_waitcnt lgkmcnt(" #n ")" ::: "memory"); SBAR(); } while (0)
; __device__ __forceinline__ void pv_tile(f32x16* o, unsigned vb, bf16x8 pa0, bf16x8 pa1, bf16x8 pa2, bf16x8 pa3) {
;     ...
;     s16x4 Al0, Al1, Al2, Al3, Ah0, Ah1, Ah2, Ah3, Bl0, Bl1, Bl2, Bl3, Bh0, Bh1, Bh2, Bh3;
;     VSET(A, 0);
;     VSET(B, 1); LWAIT(8); VMMA(A, 0); SBAR();
;     VSET(A, 2); LWAIT(8); VMMA(B, 1); SBAR();
;     VSET(B, 3); LWAIT(8); VMMA(A, 2); SBAR();
;     LWAIT(0); VMMA(B, 3);
	v_mfma_f32_32x32x16_bf16 v[112:127], v[80:83], v[172:175], v[112:127]
	v_add_f32_e64 v92, v10, v92
	v_add_f32_e64 v93, v11, v93
	v_cvt_pk_bf16_f32 v10, v10, v11
	v_add_f32_e64 v92, v12, v92
	v_add_f32_e64 v93, v13, v93
	v_cvt_pk_bf16_f32 v11, v12, v13
	v_pk_add_f32 v[92:93], v[88:89], v[92:93]
	v_cvt_pk_bf16_f32 v12, v88, v89
	v_pk_add_f32 v[214:215], v[90:91], v[92:93]
	v_cvt_pk_bf16_f32 v13, v90, v91
	v_permlane32_swap_b32_e32 v10, v12
	s_nop 0
	v_permlane32_swap_b32_e32 v11, v13
	v_mfma_f32_32x32x16_bf16 v[128:143], v[84:87], v[172:175], v[128:143]
	v_add_u32_e32 v92, v15, v249
	v_add_u32_e32 v93, v15, v250
	v_add_u32_e32 v94, v15, v251
	v_add_u32_e32 v95, v15, v252
	ds_read_b128 v[96:99], v92
	ds_read_b128 v[100:103], v93
	ds_read_b128 v[104:107], v94
	ds_read_b128 v[80:83], v92 offset:12288
	ds_read_b128 v[84:87], v93 offset:12288
	ds_read_b128 v[88:91], v94 offset:12288
	ds_read_b128 v[222:225], v95 offset:12288
	ds_read_b128 v[92:95], v95
	s_waitcnt lgkmcnt(7)
	v_mfma_f32_32x32x16_bf16 v[112:127], v[96:99], v[176:179], v[112:127]
	s_waitcnt lgkmcnt(6)
	v_mfma_f32_32x32x16_bf16 v[112:127], v[100:103], v[180:183], v[112:127]
	s_waitcnt lgkmcnt(5)
	v_mfma_f32_32x32x16_bf16 v[112:127], v[104:107], v[184:187], v[112:127]
	s_waitcnt lgkmcnt(0)
	v_mfma_f32_32x32x16_bf16 v[96:111], v[92:95], v[188:191], v[112:127]
	v_mfma_f32_32x32x16_bf16 v[128:143], v[80:83], v[176:179], v[128:143]
	v_mfma_f32_32x32x16_bf16 v[128:143], v[84:87], v[180:183], v[128:143]
	v_mfma_f32_32x32x16_bf16 v[128:143], v[88:91], v[184:187], v[128:143]
	v_mfma_f32_32x32x16_bf16 v[80:95], v[222:225], v[188:191], v[128:143]
	v_lshl_add_u32 v15, s7, 14, v237
	ds_read_b64_tr_b16 v[112:113], v15 offset:0
	ds_read_b64_tr_b16 v[114:115], v15 offset:0x800
	ds_read_b64_tr_b16 v[116:117], v15 offset:0x1000
	ds_read_b64_tr_b16 v[118:119], v15 offset:0x1800
	ds_read_b64_tr_b16 v[120:121], v15 offset:0x2000
	ds_read_b64_tr_b16 v[122:123], v15 offset:0x2800
	ds_read_b64_tr_b16 v[124:125], v15 offset:0x3000
	ds_read_b64_tr_b16 v[126:127], v15 offset:0x3800
	ds_read_b64_tr_b16 v[128:129], v15 offset:0x200
	ds_read_b64_tr_b16 v[130:131], v15 offset:0xa00
	ds_read_b64_tr_b16 v[132:133], v15 offset:0x1200
	ds_read_b64_tr_b16 v[134:135], v15 offset:0x1a00
	ds_read_b64_tr_b16 v[136:137], v15 offset:0x2200
	ds_read_b64_tr_b16 v[138:139], v15 offset:0x2a00
	ds_read_b64_tr_b16 v[140:141], v15 offset:0x3200
	ds_read_b64_tr_b16 v[142:143], v15 offset:0x3a00
	s_waitcnt lgkmcnt(8)
	s_nop 0
	v_mfma_f32_32x32x16_bf16 v[64:79], v[2:5], v[112:115], v[64:79]
	v_mfma_f32_32x32x16_bf16 v[64:79], v[6:9], v[116:119], v[64:79]
	v_mfma_f32_32x32x16_bf16 v[64:79], v[192:195], v[120:123], v[64:79]
	v_mfma_f32_32x32x16_bf16 v[64:79], v[10:13], v[124:127], v[64:79]
	ds_read_b64_tr_b16 v[112:113], v15 offset:0x400
	ds_read_b64_tr_b16 v[114:115], v15 offset:0xc00
	ds_read_b64_tr_b16 v[116:117], v15 offset:0x1400
	ds_read_b64_tr_b16 v[118:119], v15 offset:0x1c00
	ds_read_b64_tr_b16 v[120:121], v15 offset:0x2400
	ds_read_b64_tr_b16 v[122:123], v15 offset:0x2c00
	ds_read_b64_tr_b16 v[124:125], v15 offset:0x3400
	ds_read_b64_tr_b16 v[126:127], v15 offset:0x3c00
	s_waitcnt lgkmcnt(8)
	v_mfma_f32_32x32x16_bf16 v[48:63], v[2:5], v[128:131], v[48:63]
	v_mfma_f32_32x32x16_bf16 v[48:63], v[6:9], v[132:135], v[48:63]
	v_mfma_f32_32x32x16_bf16 v[48:63], v[192:195], v[136:139], v[48:63]
	v_mfma_f32_32x32x16_bf16 v[48:63], v[10:13], v[140:143], v[48:63]
	ds_read_b64_tr_b16 v[128:129], v15 offset:0x600
	ds_read_b64_tr_b16 v[130:131], v15 offset:0xe00
	ds_read_b64_tr_b16 v[132:133], v15 offset:0x1600
	ds_read_b64_tr_b16 v[134:135], v15 offset:0x1e00
	ds_read_b64_tr_b16 v[136:137], v15 offset:0x2600
	ds_read_b64_tr_b16 v[138:139], v15 offset:0x2e00
	ds_read_b64_tr_b16 v[140:141], v15 offset:0x3600
	ds_read_b64_tr_b16 v[142:143], v15 offset:0x3e00
	s_waitcnt lgkmcnt(8)
	v_mfma_f32_32x32x16_bf16 v[32:47], v[2:5], v[112:115], v[32:47]
	v_mfma_f32_32x32x16_bf16 v[32:47], v[6:9], v[116:119], v[32:47]
	v_mfma_f32_32x32x16_bf16 v[32:47], v[192:195], v[120:123], v[32:47]
	v_mfma_f32_32x32x16_bf16 v[32:47], v[10:13], v[124:127], v[32:47]
	s_waitcnt lgkmcnt(0)
	v_mfma_f32_32x32x16_bf16 v[16:31], v[2:5], v[128:131], v[16:31]
	s_waitcnt vmcnt(5)
	s_barrier
	s_add_i32 s13, s13, -1
	s_cmp_eq_u32 s13, 0
	v_mfma_f32_32x32x16_bf16 v[16:31], v[6:9], v[132:135], v[16:31]
	v_mfma_f32_32x32x16_bf16 v[16:31], v[192:195], v[136:139], v[16:31]
	v_mfma_f32_32x32x16_bf16 v[16:31], v[10:13], v[140:143], v[16:31]
	s_cbranch_scc1 .LBB0_629
	s_mov_b32 s2, s12
	s_mov_b32 s12, s9
	s_mov_b32 s9, s7
	s_branch .LBB0_624

; #define PG8_STAGE(bufoff, gbase, voff) do { _Pragma("unroll") for (int _i = 0; _i < 2; ++_i) \
;         __builtin_amdgcn_global_load_lds((const unsigned*)((const char*)(gbase) + (voff)[_i]), (PG8_LAS unsigned*)(lds + (bufoff) + ldsw + _i * 8192), 16, 0, 0); } while (0)
; #define PG8_LDA(dst, b, h) do { _Pragma("unroll") for (int m = 0; m < 4; ++m) _Pragma("unroll") for (int k = 0; k < 2; ++k) dst[m][k] = *(const PG8_LAS bf16x8*)(lds + PG8_SA(b, h) + aoff + m * 2048 + k * 1024); } while (0)
; #define PG8_LDB(dst, b, h) do { _Pragma("unroll") for (int n = 0; n < 2; ++n) _Pragma("unroll") for (int k = 0; k < 2; ++k) dst[n][k] = *(const PG8_LAS bf16x8*)(lds + PG8_SB(b, h) + boff + n * 2048 + k * 1024); } while (0)
; #define PG8_MMA(ai, bj, At, Bt) do { __builtin_amdgcn_s_setprio(1); _Pragma("unroll") for (int m = 0; m < 4; ++m) _Pragma("unroll") for (int n = 0; n < 2; ++n) _Pragma("unroll") for (int k = 0; k < 2; ++k) \
;         acc[ai][bj][m][n] = __builtin_amdgcn_mfma_f32_16x16x32_bf16(Bt[n][k], At[m][k], acc[ai][bj][m][n], 0, 0, 0); __builtin_amdgcn_s_setprio(0); } while (0)
; #define PG8_WAIT_V(n) asm volatile("s_waitcnt vmcnt(" #n ")" ::: "memory")
; #define PG8_WAIT_L(n) asm volatile("s_waitcnt lgkmcnt(" #n ")" ::: "memory")
; #define PG8_BAR __builtin_amdgcn_s_barrier()
; #define PG8_SCHED __builtin_amdgcn_sched_barrier(0)
; template <class Epi, class Sched, bool ALIGN_EPI = false, bool SP2 = false>
; __device__ __forceinline__ void gemm_phase(PG8_LAS unsigned char* lds, const Gemm g, const Sched& S, const Epi& E) {
;     ...
;             const bool last = (t == nt - 2);
;             const char* a1 = cA + (size_t)(t + 1) * kstep;
;             const char* a2 = last ? nA : cA + (size_t)(t + 2) * kstep; const char* b2 = last ? nB : cB + (size_t)(t + 2) * kstep;
;             const char* a3 = a2 + kstep; const char* b3 = b2 + kstep;
;             if (last && has_next) S.a_ready(nxt);
;             if constexpr (SP2) {
;             PG8_LDB(B0, 0, 0); PG8_LDB(B1, 0, 1); PG8_SCHED; PG8_LDA(At, 0, 0); PG8_STAGE(PG8_SA(1, 1), a1 + hstepA, voffA);
;             PG8_WAIT_V(8); PG8_WAIT_L(0); PG8_BAR; PG8_MMA(0, 0, At, B0); PG8_MMA(0, 1, At, B1); PG8_BAR; PG8_SCHED;
;             PG8_LDA(At, 0, 1); PG8_STAGE(PG8_SB(0, 0), b2, voffB); PG8_STAGE(PG8_SB(0, 1), b2 + hstepB, voffB); PG8_STAGE(PG8_SA(0, 0), a2, voffA);
.LBB0_1383:
	s_add_u32 s6, s26, 0x100
	s_addc_u32 s7, s27, 0
	s_add_i32 s2, s17, 0x100
	s_cmp_eq_u32 s65, 4
	s_cselect_b32 s41, s15, s7
	s_cselect_b32 s40, s14, s6
	v_add_u32_e32 v145, s2, v142
	s_cselect_b32 s39, s13, s63
	s_cselect_b32 s38, s61, s62
	s_add_i32 s33, s24, 0x100
	ds_read_b128 v[146:149], v145
	ds_read_b128 v[150:153], v145 offset:1024
	ds_read_b128 v[154:157], v145 offset:2048
	ds_read_b128 v[158:161], v145 offset:3072
	v_add_u32_e32 v145, s33, v142
	ds_read_b128 v[162:165], v145
	ds_read_b128 v[166:169], v145 offset:1024
	ds_read_b128 v[170:173], v145 offset:2048
	ds_read_b128 v[174:177], v145 offset:3072
	v_lshl_add_u64 v[194:195], s[26:27], 0, v[138:139]
	s_add_i32 m0, s47, 0xc000
	ds_read_b128 v[178:181], v144
	ds_read_b128 v[182:185], v144 offset:1024
	ds_read_b128 v[186:189], v144 offset:2048
	ds_read_b128 v[190:193], v144 offset:3072
	ds_read_b128 v[210:213], v144 offset:4096
	ds_read_b128 v[228:231], v144 offset:5120
	ds_read_b128 v[232:235], v144 offset:6144
	ds_read_b128 v[236:239], v144 offset:7168
	global_load_lds_dwordx4 v[194:195], off
	v_lshl_add_u64 v[194:195], s[26:27], 0, v[140:141]
	s_add_i32 m0, s47, 0xe000
	s_nop 0
	global_load_lds_dwordx4 v[194:195], off
	s_waitcnt vmcnt(8)
	s_waitcnt lgkmcnt(0)
	s_barrier
	s_setprio 1
	s_waitcnt lgkmcnt(0)
	v_mfma_f32_16x16x32_bf16 v[126:129], v[146:149], v[178:181], v[126:129]
	v_mfma_f32_16x16x32_bf16 v[126:129], v[150:153], v[182:185], v[126:129]
	v_mfma_f32_16x16x32_bf16 v[122:125], v[154:157], v[178:181], v[122:125]
	v_mfma_f32_16x16x32_bf16 v[122:125], v[158:161], v[182:185], v[122:125]
	v_mfma_f32_16x16x32_bf16 v[118:121], v[146:149], v[186:189], v[118:121]
	v_mfma_f32_16x16x32_bf16 v[118:121], v[150:153], v[190:193], v[118:121]
	v_mfma_f32_16x16x32_bf16 v[114:117], v[154:157], v[186:189], v[114:117]
	v_mfma_f32_16x16x32_bf16 v[114:117], v[158:161], v[190:193], v[114:117]
	v_mfma_f32_16x16x32_bf16 v[102:105], v[146:149], v[210:213], v[102:105]
	v_mfma_f32_16x16x32_bf16 v[102:105], v[150:153], v[228:231], v[102:105]
	v_mfma_f32_16x16x32_bf16 v[98:101], v[154:157], v[210:213], v[98:101]
	v_mfma_f32_16x16x32_bf16 v[98:101], v[158:161], v[228:231], v[98:101]
	v_mfma_f32_16x16x32_bf16 v[86:89], v[146:149], v[232:235], v[86:89]
	v_mfma_f32_16x16x32_bf16 v[86:89], v[150:153], v[236:239], v[86:89]
	v_mfma_f32_16x16x32_bf16 v[82:85], v[154:157], v[232:235], v[82:85]
	v_mfma_f32_16x16x32_bf16 v[82:85], v[158:161], v[236:239], v[82:85]
	s_setprio 0
	s_setprio 1
	v_mfma_f32_16x16x32_bf16 v[110:113], v[162:165], v[178:181], v[110:113]
	v_mfma_f32_16x16x32_bf16 v[110:113], v[166:169], v[182:185], v[110:113]
	v_mfma_f32_16x16x32_bf16 v[106:109], v[170:173], v[178:181], v[106:109]
	v_mfma_f32_16x16x32_bf16 v[106:109], v[174:177], v[182:185], v[106:109]
	v_mfma_f32_16x16x32_bf16 v[94:97], v[162:165], v[186:189], v[94:97]
	v_mfma_f32_16x16x32_bf16 v[94:97], v[166:169], v[190:193], v[94:97]
	v_mfma_f32_16x16x32_bf16 v[90:93], v[170:173], v[186:189], v[90:93]
	v_mfma_f32_16x16x32_bf16 v[90:93], v[174:177], v[190:193], v[90:93]
	v_mfma_f32_16x16x32_bf16 v[78:81], v[162:165], v[210:213], v[78:81]
	v_mfma_f32_16x16x32_bf16 v[78:81], v[166:169], v[228:231], v[78:81]
	v_mfma_f32_16x16x32_bf16 v[74:77], v[170:173], v[210:213], v[74:77]
	v_mfma_f32_16x16x32_bf16 v[74:77], v[174:177], v[228:231], v[74:77]
	v_mfma_f32_16x16x32_bf16 v[70:73], v[162:165], v[232:235], v[70:73]
	v_mfma_f32_16x16x32_bf16 v[70:73], v[166:169], v[236:239], v[70:73]
	v_mfma_f32_16x16x32_bf16 v[66:69], v[170:173], v[232:235], v[66:69]
	v_mfma_f32_16x16x32_bf16 v[66:69], v[174:177], v[236:239], v[66:69]
	s_setprio 0
	s_barrier
	s_add_i32 s2, s2, s46
	v_lshl_add_u64 v[194:195], s[38:39], 0, v[0:1]
	s_mov_b32 m0, s2
	ds_read_b128 v[178:181], v144 offset:16384
	ds_read_b128 v[182:185], v144 offset:17408
	ds_read_b128 v[186:189], v144 offset:18432
	ds_read_b128 v[190:193], v144 offset:19456
	ds_read_b128 v[210:213], v144 offset:20480
	ds_read_b128 v[228:231], v144 offset:21504
	ds_read_b128 v[232:235], v144 offset:22528
	ds_read_b128 v[236:239], v144 offset:23552
	global_load_lds_dwordx4 v[194:195], off
	s_add_i32 m0, s2, 0x2000
	s_add_u32 s26, s38, 0x20000
	v_lshl_add_u64 v[214:215], s[38:39], 0, v[132:133]
	s_addc_u32 s27, s39, 0
	s_add_i32 s2, s33, s46
	global_load_lds_dwordx4 v[214:215], off
	v_lshl_add_u64 v[222:223], s[26:27], 0, v[0:1]
	s_mov_b32 m0, s2
	v_lshl_add_u64 v[224:225], s[40:41], 0, v[134:135]
	global_load_lds_dwordx4 v[222:223], off
	v_lshl_add_u64 v[222:223], s[26:27], 0, v[132:133]
	s_add_i32 m0, s2, 0x2000
	s_nop 0
	global_load_lds_dwordx4 v[222:223], off
	v_lshl_add_u64 v[222:223], s[40:41], 0, v[136:137]
	s_mov_b32 m0, s47
	s_nop 0
	global_load_lds_dwordx4 v[222:223], off
	s_mov_b32 m0, s48
	s_nop 0
	global_load_lds_dwordx4 v[224:225], off
	s_waitcnt vmcnt(8)
	s_waitcnt lgkmcnt(0)
	s_barrier
; #define PG8_STAGE(bufoff, gbase, voff) do { _Pragma("unroll") for (int _i = 0; _i < 2; ++_i) \
;         __builtin_amdgcn_global_load_lds((const unsigned*)((const char*)(gbase) + (voff)[_i]), (PG8_LAS unsigned*)(lds + (bufoff) + ldsw + _i * 8192), 16, 0, 0); } while (0)
; #define PG8_LDA(dst, b, h) do { _Pragma("unroll") for (int m = 0; m < 4; ++m) _Pragma("unroll") for (int k = 0; k < 2; ++k) dst[m][k] = *(const PG8_LAS bf16x8*)(lds + PG8_SA(b, h) + aoff + m * 2048 + k * 1024); } while (0)
; #define PG8_LDB(dst, b, h) do { _Pragma("unroll") for (int n = 0; n < 2; ++n) _Pragma("unroll") for (int k = 0; k < 2; ++k) dst[n][k] = *(const PG8_LAS bf16x8*)(lds + PG8_SB(b, h) + boff + n * 2048 + k * 1024); } while (0)
; #define PG8_MMA(ai, bj, At, Bt) do { __builtin_amdgcn_s_setprio(1); _Pragma("unroll") for (int m = 0; m < 4; ++m) _Pragma("unroll") for (int n = 0; n < 2; ++n) _Pragma("unroll") for (int k = 0; k < 2; ++k) \
;         acc[ai][bj][m][n] = __builtin_amdgcn_mfma_f32_16x16x32_bf16(Bt[n][k], At[m][k], acc[ai][bj][m][n], 0, 0, 0); __builtin_amdgcn_s_setprio(0); } while (0)
; #define PG8_WAIT_V(n) asm volatile("s_waitcnt vmcnt(" #n ")" ::: "memory")
; #define PG8_WAIT_L(n) asm volatile("s_waitcnt lgkmcnt(" #n ")" ::: "memory")
; #define PG8_BAR __builtin_amdgcn_s_barrier()
; #define PG8_SCHED __builtin_amdgcn_sched_barrier(0)
; template <class Epi, class Sched, bool ALIGN_EPI = false, bool SP2 = false>
; __device__ __forceinline__ void gemm_phase(PG8_LAS unsigned char* lds, const Gemm g, const Sched& S, const Epi& E) {
;     ...
;             PG8_WAIT_V(8); PG8_WAIT_L(0); PG8_BAR; PG8_MMA(1, 0, At, B0); PG8_MMA(1, 1, At, B1); PG8_BAR; PG8_SCHED;
;             PG8_LDB(B0, 1, 0); PG8_LDB(B1, 1, 1); PG8_SCHED; PG8_LDA(At, 1, 0); PG8_STAGE(PG8_SA(0, 1), a2 + hstepA, voffA);
;             PG8_WAIT_V(8); PG8_WAIT_L(0); PG8_BAR; PG8_MMA(0, 0, At, B0); PG8_MMA(0, 1, At, B1); PG8_BAR; PG8_SCHED;
	s_setprio 1
	s_waitcnt lgkmcnt(0)
	v_mfma_f32_16x16x32_bf16 v[62:65], v[146:149], v[178:181], v[62:65]
	v_mfma_f32_16x16x32_bf16 v[62:65], v[150:153], v[182:185], v[62:65]
	v_mfma_f32_16x16x32_bf16 v[58:61], v[154:157], v[178:181], v[58:61]
	v_mfma_f32_16x16x32_bf16 v[58:61], v[158:161], v[182:185], v[58:61]
	v_mfma_f32_16x16x32_bf16 v[54:57], v[146:149], v[186:189], v[54:57]
	v_mfma_f32_16x16x32_bf16 v[54:57], v[150:153], v[190:193], v[54:57]
	v_mfma_f32_16x16x32_bf16 v[50:53], v[154:157], v[186:189], v[50:53]
	v_mfma_f32_16x16x32_bf16 v[50:53], v[158:161], v[190:193], v[50:53]
	v_mfma_f32_16x16x32_bf16 v[38:41], v[146:149], v[210:213], v[38:41]
	v_mfma_f32_16x16x32_bf16 v[38:41], v[150:153], v[228:231], v[38:41]
	v_mfma_f32_16x16x32_bf16 v[34:37], v[154:157], v[210:213], v[34:37]
	v_mfma_f32_16x16x32_bf16 v[34:37], v[158:161], v[228:231], v[34:37]
	v_mfma_f32_16x16x32_bf16 v[22:25], v[146:149], v[232:235], v[22:25]
	v_mfma_f32_16x16x32_bf16 v[22:25], v[150:153], v[236:239], v[22:25]
	v_mfma_f32_16x16x32_bf16 v[18:21], v[154:157], v[232:235], v[18:21]
	v_mfma_f32_16x16x32_bf16 v[18:21], v[158:161], v[236:239], v[18:21]
	s_setprio 0
	s_setprio 1
	v_mfma_f32_16x16x32_bf16 v[46:49], v[162:165], v[178:181], v[46:49]
	v_mfma_f32_16x16x32_bf16 v[46:49], v[166:169], v[182:185], v[46:49]
	v_mfma_f32_16x16x32_bf16 v[42:45], v[170:173], v[178:181], v[42:45]
	v_mfma_f32_16x16x32_bf16 v[42:45], v[174:177], v[182:185], v[42:45]
	v_mfma_f32_16x16x32_bf16 v[30:33], v[162:165], v[186:189], v[30:33]
	v_mfma_f32_16x16x32_bf16 v[30:33], v[166:169], v[190:193], v[30:33]
	v_mfma_f32_16x16x32_bf16 v[26:29], v[170:173], v[186:189], v[26:29]
	v_mfma_f32_16x16x32_bf16 v[26:29], v[174:177], v[190:193], v[26:29]
	v_mfma_f32_16x16x32_bf16 v[14:17], v[162:165], v[210:213], v[14:17]
	v_mfma_f32_16x16x32_bf16 v[14:17], v[166:169], v[228:231], v[14:17]
	v_mfma_f32_16x16x32_bf16 v[10:13], v[170:173], v[210:213], v[10:13]
	v_mfma_f32_16x16x32_bf16 v[10:13], v[174:177], v[228:231], v[10:13]
	v_mfma_f32_16x16x32_bf16 v[6:9], v[162:165], v[232:235], v[6:9]
	v_mfma_f32_16x16x32_bf16 v[6:9], v[166:169], v[236:239], v[6:9]
	v_mfma_f32_16x16x32_bf16 v[2:5], v[170:173], v[232:235], v[2:5]
	v_mfma_f32_16x16x32_bf16 v[2:5], v[174:177], v[236:239], v[2:5]
	s_setprio 0
	s_barrier
	s_add_i32 s2, s87, 0x100
	v_add_u32_e32 v145, s2, v142
	s_add_i32 s33, s69, 0x100
	ds_read_b128 v[146:149], v145
	ds_read_b128 v[150:153], v145 offset:1024
	ds_read_b128 v[154:157], v145 offset:2048
	ds_read_b128 v[158:161], v145 offset:3072
	v_add_u32_e32 v145, s33, v142
	ds_read_b128 v[162:165], v145
	ds_read_b128 v[166:169], v145 offset:1024
	ds_read_b128 v[170:173], v145 offset:2048
	ds_read_b128 v[174:177], v145 offset:3072
	s_add_u32 s26, s40, 0x130000
	s_addc_u32 s27, s41, 0
	s_mov_b32 m0, s49
	v_lshl_add_u64 v[240:241], s[26:27], 0, v[136:137]
	ds_read_b128 v[178:181], v144 offset:32768
	ds_read_b128 v[182:185], v144 offset:33792
	ds_read_b128 v[186:189], v144 offset:34816
	ds_read_b128 v[190:193], v144 offset:35840
	ds_read_b128 v[210:213], v144 offset:36864
	ds_read_b128 v[228:231], v144 offset:37888
	ds_read_b128 v[232:235], v144 offset:38912
	ds_read_b128 v[236:239], v144 offset:39936
	global_load_lds_dwordx4 v[240:241], off
	v_lshl_add_u64 v[240:241], s[26:27], 0, v[134:135]
	s_mov_b32 m0, s50
	s_nop 0
	global_load_lds_dwordx4 v[240:241], off
	s_waitcnt vmcnt(8)
	s_waitcnt lgkmcnt(0)
	s_barrier
	s_setprio 1
	s_waitcnt lgkmcnt(0)
	v_mfma_f32_16x16x32_bf16 v[126:129], v[146:149], v[178:181], v[126:129]
	v_mfma_f32_16x16x32_bf16 v[126:129], v[150:153], v[182:185], v[126:129]
	v_mfma_f32_16x16x32_bf16 v[122:125], v[154:157], v[178:181], v[122:125]
	v_mfma_f32_16x16x32_bf16 v[122:125], v[158:161], v[182:185], v[122:125]
	v_mfma_f32_16x16x32_bf16 v[118:121], v[146:149], v[186:189], v[118:121]
	v_mfma_f32_16x16x32_bf16 v[118:121], v[150:153], v[190:193], v[118:121]
	v_mfma_f32_16x16x32_bf16 v[114:117], v[154:157], v[186:189], v[114:117]
	v_mfma_f32_16x16x32_bf16 v[114:117], v[158:161], v[190:193], v[114:117]
	v_mfma_f32_16x16x32_bf16 v[102:105], v[146:149], v[210:213], v[102:105]
	v_mfma_f32_16x16x32_bf16 v[102:105], v[150:153], v[228:231], v[102:105]
	v_mfma_f32_16x16x32_bf16 v[98:101], v[154:157], v[210:213], v[98:101]
	v_mfma_f32_16x16x32_bf16 v[98:101], v[158:161], v[228:231], v[98:101]
	v_mfma_f32_16x16x32_bf16 v[86:89], v[146:149], v[232:235], v[86:89]
	v_mfma_f32_16x16x32_bf16 v[86:89], v[150:153], v[236:239], v[86:89]
	v_mfma_f32_16x16x32_bf16 v[82:85], v[154:157], v[232:235], v[82:85]
	v_mfma_f32_16x16x32_bf16 v[82:85], v[158:161], v[236:239], v[82:85]
	s_setprio 0
	s_setprio 1
	v_mfma_f32_16x16x32_bf16 v[110:113], v[162:165], v[178:181], v[110:113]
	v_mfma_f32_16x16x32_bf16 v[110:113], v[166:169], v[182:185], v[110:113]
	v_mfma_f32_16x16x32_bf16 v[106:109], v[170:173], v[178:181], v[106:109]
	v_mfma_f32_16x16x32_bf16 v[106:109], v[174:177], v[182:185], v[106:109]
	v_mfma_f32_16x16x32_bf16 v[94:97], v[162:165], v[186:189], v[94:97]
	v_mfma_f32_16x16x32_bf16 v[94:97], v[166:169], v[190:193], v[94:97]
	v_mfma_f32_16x16x32_bf16 v[90:93], v[170:173], v[186:189], v[90:93]
	v_mfma_f32_16x16x32_bf16 v[90:93], v[174:177], v[190:193], v[90:93]
	v_mfma_f32_16x16x32_bf16 v[78:81], v[162:165], v[210:213], v[78:81]
	v_mfma_f32_16x16x32_bf16 v[78:81], v[166:169], v[228:231], v[78:81]
	v_mfma_f32_16x16x32_bf16 v[74:77], v[170:173], v[210:213], v[74:77]
	v_mfma_f32_16x16x32_bf16 v[74:77], v[174:177], v[228:231], v[74:77]
	v_mfma_f32_16x16x32_bf16 v[70:73], v[162:165], v[232:235], v[70:73]
	v_mfma_f32_16x16x32_bf16 v[70:73], v[166:169], v[236:239], v[70:73]
	v_mfma_f32_16x16x32_bf16 v[66:69], v[170:173], v[232:235], v[66:69]
	v_mfma_f32_16x16x32_bf16 v[66:69], v[174:177], v[236:239], v[66:69]
	s_setprio 0
	s_barrier
; #define PG8_STAGE(bufoff, gbase, voff) do { _Pragma("unroll") for (int _i = 0; _i < 2; ++_i) \
;         __builtin_amdgcn_global_load_lds((const unsigned*)((const char*)(gbase) + (voff)[_i]), (PG8_LAS unsigned*)(lds + (bufoff) + ldsw + _i * 8192), 16, 0, 0); } while (0)
; #define PG8_LDA(dst, b, h) do { _Pragma("unroll") for (int m = 0; m < 4; ++m) _Pragma("unroll") for (int k = 0; k < 2; ++k) dst[m][k] = *(const PG8_LAS bf16x8*)(lds + PG8_SA(b, h) + aoff + m * 2048 + k * 1024); } while (0)
; #define PG8_MMA(ai, bj, At, Bt) do { __builtin_amdgcn_s_setprio(1); _Pragma("unroll") for (int m = 0; m < 4; ++m) _Pragma("unroll") for (int n = 0; n < 2; ++n) _Pragma("unroll") for (int k = 0; k < 2; ++k) \
;         acc[ai][bj][m][n] = __builtin_amdgcn_mfma_f32_16x16x32_bf16(Bt[n][k], At[m][k], acc[ai][bj][m][n], 0, 0, 0); __builtin_amdgcn_s_setprio(0); } while (0)
; #define PG8_WAIT_V(n) asm volatile("s_waitcnt vmcnt(" #n ")" ::: "memory")
; #define PG8_WAIT_L(n) asm volatile("s_waitcnt lgkmcnt(" #n ")" ::: "memory")
; #define PG8_BAR __builtin_amdgcn_s_barrier()
; #define PG8_SCHED __builtin_amdgcn_sched_barrier(0)
; template <class Epi, class Sched, bool ALIGN_EPI = false, bool SP2 = false>
; __device__ __forceinline__ void gemm_phase(PG8_LAS unsigned char* lds, const Gemm g, const Sched& S, const Epi& E) {
;     ...
;             PG8_LDA(At, 1, 1); PG8_STAGE(PG8_SB(1, 0), b3, voffB); PG8_STAGE(PG8_SB(1, 1), b3 + hstepB, voffB); PG8_STAGE(PG8_SA(1, 0), a3, voffA);
;             PG8_WAIT_V(8); PG8_WAIT_L(0); PG8_BAR; PG8_MMA(1, 0, At, B0); PG8_MMA(1, 1, At, B1); PG8_BAR; PG8_SCHED;
	s_add_i32 s2, s2, s46
	v_lshl_add_u64 v[194:195], v[194:195], 0, s[94:95]
	s_mov_b32 m0, s2
	ds_read_b128 v[178:181], v144 offset:49152
	ds_read_b128 v[182:185], v144 offset:50176
	ds_read_b128 v[186:189], v144 offset:51200
	ds_read_b128 v[190:193], v144 offset:52224
	ds_read_b128 v[210:213], v144 offset:53248
	ds_read_b128 v[228:231], v144 offset:54272
	ds_read_b128 v[232:235], v144 offset:55296
	ds_read_b128 v[236:239], v144 offset:56320
	global_load_lds_dwordx4 v[194:195], off
	s_add_i32 m0, s2, 0x2000
	s_add_u32 s26, s38, 0x20080
	v_lshl_add_u64 v[194:195], v[214:215], 0, s[94:95]
	s_addc_u32 s27, s39, 0
	s_add_i32 s2, s33, s46
	global_load_lds_dwordx4 v[194:195], off
	v_lshl_add_u64 v[194:195], s[26:27], 0, v[0:1]
	s_mov_b32 m0, s2
	s_nop 0
	global_load_lds_dwordx4 v[194:195], off
	v_lshl_add_u64 v[194:195], s[26:27], 0, v[132:133]
	s_add_i32 m0, s2, 0x2000
	s_nop 0
	global_load_lds_dwordx4 v[194:195], off
	v_lshl_add_u64 v[194:195], v[222:223], 0, s[94:95]
	s_mov_b32 m0, s51
	s_nop 0
	global_load_lds_dwordx4 v[194:195], off
	v_lshl_add_u64 v[194:195], v[224:225], 0, s[94:95]
	s_mov_b32 m0, s58
	s_nop 0
	global_load_lds_dwordx4 v[194:195], off
	s_waitcnt vmcnt(8)
	s_waitcnt lgkmcnt(0)
	s_barrier
	s_setprio 1
	s_waitcnt lgkmcnt(0)
	v_mfma_f32_16x16x32_bf16 v[62:65], v[146:149], v[178:181], v[62:65]
	v_mfma_f32_16x16x32_bf16 v[62:65], v[150:153], v[182:185], v[62:65]
	v_mfma_f32_16x16x32_bf16 v[58:61], v[154:157], v[178:181], v[58:61]
	v_mfma_f32_16x16x32_bf16 v[58:61], v[158:161], v[182:185], v[58:61]
	v_mfma_f32_16x16x32_bf16 v[54:57], v[146:149], v[186:189], v[54:57]
	v_mfma_f32_16x16x32_bf16 v[54:57], v[150:153], v[190:193], v[54:57]
	v_mfma_f32_16x16x32_bf16 v[50:53], v[154:157], v[186:189], v[50:53]
	v_mfma_f32_16x16x32_bf16 v[50:53], v[158:161], v[190:193], v[50:53]
	v_mfma_f32_16x16x32_bf16 v[38:41], v[146:149], v[210:213], v[38:41]
	v_mfma_f32_16x16x32_bf16 v[38:41], v[150:153], v[228:231], v[38:41]
	v_mfma_f32_16x16x32_bf16 v[34:37], v[154:157], v[210:213], v[34:37]
	v_mfma_f32_16x16x32_bf16 v[34:37], v[158:161], v[228:231], v[34:37]
	v_mfma_f32_16x16x32_bf16 v[22:25], v[146:149], v[232:235], v[22:25]
	v_mfma_f32_16x16x32_bf16 v[22:25], v[150:153], v[236:239], v[22:25]
	v_mfma_f32_16x16x32_bf16 v[18:21], v[154:157], v[232:235], v[18:21]
	v_mfma_f32_16x16x32_bf16 v[18:21], v[158:161], v[236:239], v[18:21]
	s_setprio 0
	s_setprio 1
	v_mfma_f32_16x16x32_bf16 v[46:49], v[162:165], v[178:181], v[46:49]
	v_mfma_f32_16x16x32_bf16 v[46:49], v[166:169], v[182:185], v[46:49]
	v_mfma_f32_16x16x32_bf16 v[42:45], v[170:173], v[178:181], v[42:45]
	v_mfma_f32_16x16x32_bf16 v[42:45], v[174:177], v[182:185], v[42:45]
	v_mfma_f32_16x16x32_bf16 v[30:33], v[162:165], v[186:189], v[30:33]
	v_mfma_f32_16x16x32_bf16 v[30:33], v[166:169], v[190:193], v[30:33]
	v_mfma_f32_16x16x32_bf16 v[26:29], v[170:173], v[186:189], v[26:29]
	v_mfma_f32_16x16x32_bf16 v[26:29], v[174:177], v[190:193], v[26:29]
	v_mfma_f32_16x16x32_bf16 v[14:17], v[162:165], v[210:213], v[14:17]
	v_mfma_f32_16x16x32_bf16 v[14:17], v[166:169], v[228:231], v[14:17]
	v_mfma_f32_16x16x32_bf16 v[10:13], v[170:173], v[210:213], v[10:13]
	v_mfma_f32_16x16x32_bf16 v[10:13], v[174:177], v[228:231], v[10:13]
	v_mfma_f32_16x16x32_bf16 v[6:9], v[162:165], v[232:235], v[6:9]
	v_mfma_f32_16x16x32_bf16 v[6:9], v[166:169], v[236:239], v[6:9]
	v_mfma_f32_16x16x32_bf16 v[2:5], v[170:173], v[232:235], v[2:5]
	v_mfma_f32_16x16x32_bf16 v[2:5], v[174:177], v[236:239], v[2:5]
	s_setprio 0
	s_barrier
	s_add_i32 s65, s65, 2
	s_add_u32 s62, s62, 0x100
	s_addc_u32 s63, s63, 0
	s_cmp_gt_u32 s65, 5
	s_mov_b64 s[26:27], s[6:7]
	s_cbranch_scc0 .LBB0_1383
	s_and_b64 vcc, exec, s[10:11]
	s_cbranch_vccz .LBB0_1386
	s_barrier

; #define PG8_STAGE(bufoff, gbase, voff) do { _Pragma("unroll") for (int _i = 0; _i < 2; ++_i) \
;         __builtin_amdgcn_global_load_lds((const unsigned*)((const char*)(gbase) + (voff)[_i]), (PG8_LAS unsigned*)(lds + (bufoff) + ldsw + _i * 8192), 16, 0, 0); } while (0)
; #define PG8_LDA(dst, b, h) do { _Pragma("unroll") for (int m = 0; m < 4; ++m) _Pragma("unroll") for (int k = 0; k < 2; ++k) dst[m][k] = *(const PG8_LAS bf16x8*)(lds + PG8_SA(b, h) + aoff + m * 2048 + k * 1024); } while (0)
; #define PG8_LDB(dst, b, h) do { _Pragma("unroll") for (int n = 0; n < 2; ++n) _Pragma("unroll") for (int k = 0; k < 2; ++k) dst[n][k] = *(const PG8_LAS bf16x8*)(lds + PG8_SB(b, h) + boff + n * 2048 + k * 1024); } while (0)
; #define PG8_MMA(ai, bj, At, Bt) do { __builtin_amdgcn_s_setprio(1); _Pragma("unroll") for (int m = 0; m < 4; ++m) _Pragma("unroll") for (int n = 0; n < 2; ++n) _Pragma("unroll") for (int k = 0; k < 2; ++k) \
;         acc[ai][bj][m][n] = __builtin_amdgcn_mfma_f32_16x16x32_bf16(Bt[n][k], At[m][k], acc[ai][bj][m][n], 0, 0, 0); __builtin_amdgcn_s_setprio(0); } while (0)
; #define PG8_WAIT_V(n) asm volatile("s_waitcnt vmcnt(" #n ")" ::: "memory")
; #define PG8_WAIT_L(n) asm volatile("s_waitcnt lgkmcnt(" #n ")" ::: "memory")
; #define PG8_BAR __builtin_amdgcn_s_barrier()
; #define PG8_SCHED __builtin_amdgcn_sched_barrier(0)
; template <class Epi, class Sched, bool ALIGN_EPI = false, bool SP2 = false>
; __device__ __forceinline__ void gemm_phase(PG8_LAS unsigned char* lds, const Gemm g, const Sched& S, const Epi& E) {
;     ...
;             const bool last = (t == nt - 2);
;             const char* a1 = cA + (size_t)(t + 1) * kstep;
;             const char* a2 = last ? nA : cA + (size_t)(t + 2) * kstep; const char* b2 = last ? nB : cB + (size_t)(t + 2) * kstep;
;             const char* a3 = a2 + kstep; const char* b3 = b2 + kstep;
;             if (last && has_next) S.a_ready(nxt);
;             if constexpr (SP2) {
;             PG8_LDB(B0, 0, 0); PG8_LDB(B1, 0, 1); PG8_SCHED; PG8_LDA(At, 0, 0); PG8_STAGE(PG8_SA(1, 1), a1 + hstepA, voffA);
;             PG8_WAIT_V(8); PG8_WAIT_L(0); PG8_BAR; PG8_MMA(0, 0, At, B0); PG8_MMA(0, 1, At, B1); PG8_BAR; PG8_SCHED;
;             PG8_LDA(At, 0, 1); PG8_STAGE(PG8_SB(0, 0), b2, voffB); PG8_STAGE(PG8_SB(0, 1), b2 + hstepB, voffB); PG8_STAGE(PG8_SA(0, 0), a2, voffA);
.LBB0_1403:
	s_add_u32 s2, s38, s44
	s_addc_u32 s33, s39, 0
	s_add_u32 s45, s2, 0x100
	s_addc_u32 s48, s33, 0
	s_and_b64 s[46:47], s[42:43], exec
	s_cselect_b32 s47, s27, s48
	s_cselect_b32 s46, s26, s45
	s_add_u32 s44, s18, s44
	s_addc_u32 s45, s19, 0
	s_add_u32 s44, s44, 0x100
	s_addc_u32 s45, s45, 0
	s_add_i32 s68, s17, 0x100
	s_and_b64 s[42:43], s[42:43], exec
	s_cselect_b32 s49, s15, s45
	s_cselect_b32 s48, s91, s44
	s_add_i32 s43, s24, 0x100
	s_add_u32 s52, s2, 0x130080
	s_addc_u32 s53, s33, 0
	s_add_i32 s84, s68, s59
	s_add_i32 m0, s82, 0xc000
	s_add_i32 s70, s82, 0xe000
	s_add_i32 s79, s84, 0x2000
	v_add_u32_e32 v141, s68, v138
	s_add_u32 s50, s48, 0x10000
	ds_read_b128 v[142:145], v141
	ds_read_b128 v[146:149], v141 offset:1024
	ds_read_b128 v[150:153], v141 offset:2048
	ds_read_b128 v[154:157], v141 offset:3072
	v_add_u32_e32 v141, s43, v138
	s_addc_u32 s51, s49, 0
	s_add_i32 s85, s43, s59
	ds_read_b128 v[158:161], v141
	ds_read_b128 v[162:165], v141 offset:1024
	ds_read_b128 v[166:169], v141 offset:2048
	ds_read_b128 v[170:173], v141 offset:3072
	s_add_i32 s78, s85, 0x2000
	s_add_i32 vcc_hi, s87, 0x100
	s_add_i32 s2, s69, 0x100
	s_add_u32 s44, s46, 0x130000
	s_addc_u32 s45, s47, 0
	s_add_i32 vcc_lo, vcc_hi, s59
	s_add_i32 s86, vcc_lo, 0x2000
	s_add_u32 s42, s48, 0x10080
	s_addc_u32 s43, s49, 0
	s_add_i32 s33, s2, s59
	s_add_i32 s68, s33, 0x2000
	v_lshl_add_u64 v[194:195], s[52:53], 0, v[136:137]
	ds_read_b128 v[174:177], v140
	ds_read_b128 v[178:181], v140 offset:1024
	ds_read_b128 v[182:185], v140 offset:2048
	ds_read_b128 v[186:189], v140 offset:3072
	ds_read_b128 v[190:193], v140 offset:4096
	ds_read_b128 v[210:213], v140 offset:5120
	ds_read_b128 v[228:231], v140 offset:6144
	ds_read_b128 v[232:235], v140 offset:7168
	global_load_lds_dwordx4 v[194:195], off
	v_lshl_add_u64 v[194:195], s[52:53], 0, v[134:135]
	s_mov_b32 m0, s70
	s_nop 0
	global_load_lds_dwordx4 v[194:195], off
	s_waitcnt vmcnt(8)
	s_waitcnt lgkmcnt(0)
	s_barrier
	s_setprio 1
	s_waitcnt lgkmcnt(0)
	v_mfma_f32_16x16x32_bf16 v[126:129], v[142:145], v[174:177], v[126:129]
	v_mfma_f32_16x16x32_bf16 v[126:129], v[146:149], v[178:181], v[126:129]
	v_mfma_f32_16x16x32_bf16 v[122:125], v[150:153], v[174:177], v[122:125]
	v_mfma_f32_16x16x32_bf16 v[122:125], v[154:157], v[178:181], v[122:125]
	v_mfma_f32_16x16x32_bf16 v[118:121], v[142:145], v[182:185], v[118:121]
	v_mfma_f32_16x16x32_bf16 v[118:121], v[146:149], v[186:189], v[118:121]
	v_mfma_f32_16x16x32_bf16 v[114:117], v[150:153], v[182:185], v[114:117]
	v_mfma_f32_16x16x32_bf16 v[114:117], v[154:157], v[186:189], v[114:117]
	v_mfma_f32_16x16x32_bf16 v[102:105], v[142:145], v[190:193], v[102:105]
	v_mfma_f32_16x16x32_bf16 v[102:105], v[146:149], v[210:213], v[102:105]
	v_mfma_f32_16x16x32_bf16 v[98:101], v[150:153], v[190:193], v[98:101]
	v_mfma_f32_16x16x32_bf16 v[98:101], v[154:157], v[210:213], v[98:101]
	v_mfma_f32_16x16x32_bf16 v[86:89], v[142:145], v[228:231], v[86:89]
	v_mfma_f32_16x16x32_bf16 v[86:89], v[146:149], v[232:235], v[86:89]
	v_mfma_f32_16x16x32_bf16 v[82:85], v[150:153], v[228:231], v[82:85]
	v_mfma_f32_16x16x32_bf16 v[82:85], v[154:157], v[232:235], v[82:85]
	s_setprio 0
	s_setprio 1
	v_mfma_f32_16x16x32_bf16 v[110:113], v[158:161], v[174:177], v[110:113]
	v_mfma_f32_16x16x32_bf16 v[110:113], v[162:165], v[178:181], v[110:113]
	v_mfma_f32_16x16x32_bf16 v[106:109], v[166:169], v[174:177], v[106:109]
	v_mfma_f32_16x16x32_bf16 v[106:109], v[170:173], v[178:181], v[106:109]
	v_mfma_f32_16x16x32_bf16 v[94:97], v[158:161], v[182:185], v[94:97]
	v_mfma_f32_16x16x32_bf16 v[94:97], v[162:165], v[186:189], v[94:97]
	v_mfma_f32_16x16x32_bf16 v[90:93], v[166:169], v[182:185], v[90:93]
	v_mfma_f32_16x16x32_bf16 v[90:93], v[170:173], v[186:189], v[90:93]
	v_mfma_f32_16x16x32_bf16 v[78:81], v[158:161], v[190:193], v[78:81]
	v_mfma_f32_16x16x32_bf16 v[78:81], v[162:165], v[210:213], v[78:81]
	v_mfma_f32_16x16x32_bf16 v[74:77], v[166:169], v[190:193], v[74:77]
	v_mfma_f32_16x16x32_bf16 v[74:77], v[170:173], v[210:213], v[74:77]
	v_mfma_f32_16x16x32_bf16 v[70:73], v[158:161], v[228:231], v[70:73]
	v_mfma_f32_16x16x32_bf16 v[70:73], v[162:165], v[232:235], v[70:73]
	v_mfma_f32_16x16x32_bf16 v[66:69], v[166:169], v[228:231], v[66:69]
	v_mfma_f32_16x16x32_bf16 v[66:69], v[170:173], v[232:235], v[66:69]
	s_setprio 0
	s_barrier
	s_mov_b32 m0, s84
	v_lshl_add_u64 v[194:195], s[48:49], 0, v[0:1]
	ds_read_b128 v[174:177], v140 offset:16384
	ds_read_b128 v[178:181], v140 offset:17408
	ds_read_b128 v[182:185], v140 offset:18432
	ds_read_b128 v[186:189], v140 offset:19456
	ds_read_b128 v[190:193], v140 offset:20480
	ds_read_b128 v[210:213], v140 offset:21504
	ds_read_b128 v[228:231], v140 offset:22528
	ds_read_b128 v[232:235], v140 offset:23552
	global_load_lds_dwordx4 v[194:195], off
	v_lshl_add_u64 v[214:215], s[48:49], 0, v[132:133]
	s_mov_b32 m0, s79
	v_lshl_add_u64 v[222:223], s[50:51], 0, v[0:1]
	global_load_lds_dwordx4 v[214:215], off
	s_mov_b32 m0, s85
	v_lshl_add_u64 v[224:225], s[46:47], 0, v[134:135]
	global_load_lds_dwordx4 v[222:223], off
	v_lshl_add_u64 v[222:223], s[50:51], 0, v[132:133]
	s_mov_b32 m0, s78
	s_nop 0
	global_load_lds_dwordx4 v[222:223], off
	v_lshl_add_u64 v[222:223], s[46:47], 0, v[136:137]
	s_mov_b32 m0, s82
	s_nop 0
	global_load_lds_dwordx4 v[222:223], off
	s_mov_b32 m0, s72
	s_nop 0
	global_load_lds_dwordx4 v[224:225], off
	s_waitcnt vmcnt(8)
	s_waitcnt lgkmcnt(0)
	s_barrier
; #define PG8_STAGE(bufoff, gbase, voff) do { _Pragma("unroll") for (int _i = 0; _i < 2; ++_i) \
;         __builtin_amdgcn_global_load_lds((const unsigned*)((const char*)(gbase) + (voff)[_i]), (PG8_LAS unsigned*)(lds + (bufoff) + ldsw + _i * 8192), 16, 0, 0); } while (0)
; #define PG8_LDA(dst, b, h) do { _Pragma("unroll") for (int m = 0; m < 4; ++m) _Pragma("unroll") for (int k = 0; k < 2; ++k) dst[m][k] = *(const PG8_LAS bf16x8*)(lds + PG8_SA(b, h) + aoff + m * 2048 + k * 1024); } while (0)
; #define PG8_LDB(dst, b, h) do { _Pragma("unroll") for (int n = 0; n < 2; ++n) _Pragma("unroll") for (int k = 0; k < 2; ++k) dst[n][k] = *(const PG8_LAS bf16x8*)(lds + PG8_SB(b, h) + boff + n * 2048 + k * 1024); } while (0)
; #define PG8_MMA(ai, bj, At, Bt) do { __builtin_amdgcn_s_setprio(1); _Pragma("unroll") for (int m = 0; m < 4; ++m) _Pragma("unroll") for (int n = 0; n < 2; ++n) _Pragma("unroll") for (int k = 0; k < 2; ++k) \
;         acc[ai][bj][m][n] = __builtin_amdgcn_mfma_f32_16x16x32_bf16(Bt[n][k], At[m][k], acc[ai][bj][m][n], 0, 0, 0); __builtin_amdgcn_s_setprio(0); } while (0)
; #define PG8_WAIT_V(n) asm volatile("s_waitcnt vmcnt(" #n ")" ::: "memory")
; #define PG8_WAIT_L(n) asm volatile("s_waitcnt lgkmcnt(" #n ")" ::: "memory")
; #define PG8_BAR __builtin_amdgcn_s_barrier()
; #define PG8_SCHED __builtin_amdgcn_sched_barrier(0)
; template <class Epi, class Sched, bool ALIGN_EPI = false, bool SP2 = false>
; __device__ __forceinline__ void gemm_phase(PG8_LAS unsigned char* lds, const Gemm g, const Sched& S, const Epi& E) {
;     ...
;             PG8_WAIT_V(8); PG8_WAIT_L(0); PG8_BAR; PG8_MMA(1, 0, At, B0); PG8_MMA(1, 1, At, B1); PG8_BAR; PG8_SCHED;
;             PG8_LDB(B0, 1, 0); PG8_LDB(B1, 1, 1); PG8_SCHED; PG8_LDA(At, 1, 0); PG8_STAGE(PG8_SA(0, 1), a2 + hstepA, voffA);
;             PG8_WAIT_V(8); PG8_WAIT_L(0); PG8_BAR; PG8_MMA(0, 0, At, B0); PG8_MMA(0, 1, At, B1); PG8_BAR; PG8_SCHED;
	s_setprio 1
	s_waitcnt lgkmcnt(0)
	v_mfma_f32_16x16x32_bf16 v[62:65], v[142:145], v[174:177], v[62:65]
	v_mfma_f32_16x16x32_bf16 v[62:65], v[146:149], v[178:181], v[62:65]
	v_mfma_f32_16x16x32_bf16 v[58:61], v[150:153], v[174:177], v[58:61]
	v_mfma_f32_16x16x32_bf16 v[58:61], v[154:157], v[178:181], v[58:61]
	v_mfma_f32_16x16x32_bf16 v[54:57], v[142:145], v[182:185], v[54:57]
	v_mfma_f32_16x16x32_bf16 v[54:57], v[146:149], v[186:189], v[54:57]
	v_mfma_f32_16x16x32_bf16 v[50:53], v[150:153], v[182:185], v[50:53]
	v_mfma_f32_16x16x32_bf16 v[50:53], v[154:157], v[186:189], v[50:53]
	v_mfma_f32_16x16x32_bf16 v[38:41], v[142:145], v[190:193], v[38:41]
	v_mfma_f32_16x16x32_bf16 v[38:41], v[146:149], v[210:213], v[38:41]
	v_mfma_f32_16x16x32_bf16 v[34:37], v[150:153], v[190:193], v[34:37]
	v_mfma_f32_16x16x32_bf16 v[34:37], v[154:157], v[210:213], v[34:37]
	v_mfma_f32_16x16x32_bf16 v[22:25], v[142:145], v[228:231], v[22:25]
	v_mfma_f32_16x16x32_bf16 v[22:25], v[146:149], v[232:235], v[22:25]
	v_mfma_f32_16x16x32_bf16 v[18:21], v[150:153], v[228:231], v[18:21]
	v_mfma_f32_16x16x32_bf16 v[18:21], v[154:157], v[232:235], v[18:21]
	s_setprio 0
	s_setprio 1
	v_mfma_f32_16x16x32_bf16 v[46:49], v[158:161], v[174:177], v[46:49]
	v_mfma_f32_16x16x32_bf16 v[46:49], v[162:165], v[178:181], v[46:49]
	v_mfma_f32_16x16x32_bf16 v[42:45], v[166:169], v[174:177], v[42:45]
	v_mfma_f32_16x16x32_bf16 v[42:45], v[170:173], v[178:181], v[42:45]
	v_mfma_f32_16x16x32_bf16 v[30:33], v[158:161], v[182:185], v[30:33]
	v_mfma_f32_16x16x32_bf16 v[30:33], v[162:165], v[186:189], v[30:33]
	v_mfma_f32_16x16x32_bf16 v[26:29], v[166:169], v[182:185], v[26:29]
	v_mfma_f32_16x16x32_bf16 v[26:29], v[170:173], v[186:189], v[26:29]
	v_mfma_f32_16x16x32_bf16 v[14:17], v[158:161], v[190:193], v[14:17]
	v_mfma_f32_16x16x32_bf16 v[14:17], v[162:165], v[210:213], v[14:17]
	v_mfma_f32_16x16x32_bf16 v[10:13], v[166:169], v[190:193], v[10:13]
	v_mfma_f32_16x16x32_bf16 v[10:13], v[170:173], v[210:213], v[10:13]
	v_mfma_f32_16x16x32_bf16 v[6:9], v[158:161], v[228:231], v[6:9]
	v_mfma_f32_16x16x32_bf16 v[6:9], v[162:165], v[232:235], v[6:9]
	v_mfma_f32_16x16x32_bf16 v[2:5], v[166:169], v[228:231], v[2:5]
	v_mfma_f32_16x16x32_bf16 v[2:5], v[170:173], v[232:235], v[2:5]
	s_setprio 0
	s_barrier
	v_add_u32_e32 v141, vcc_hi, v138
	ds_read_b128 v[142:145], v141
	ds_read_b128 v[146:149], v141 offset:1024
	ds_read_b128 v[150:153], v141 offset:2048
	ds_read_b128 v[154:157], v141 offset:3072
	v_add_u32_e32 v141, s2, v138
	ds_read_b128 v[158:161], v141
	ds_read_b128 v[162:165], v141 offset:1024
	ds_read_b128 v[166:169], v141 offset:2048
	ds_read_b128 v[170:173], v141 offset:3072
	s_mov_b32 m0, s73
	v_lshl_add_u64 v[236:237], s[44:45], 0, v[136:137]
	ds_read_b128 v[174:177], v140 offset:32768
	ds_read_b128 v[178:181], v140 offset:33792
	ds_read_b128 v[182:185], v140 offset:34816
	ds_read_b128 v[186:189], v140 offset:35840
	ds_read_b128 v[190:193], v140 offset:36864
	ds_read_b128 v[210:213], v140 offset:37888
	ds_read_b128 v[228:231], v140 offset:38912
	ds_read_b128 v[232:235], v140 offset:39936
	global_load_lds_dwordx4 v[236:237], off
	v_lshl_add_u64 v[236:237], s[44:45], 0, v[134:135]
	s_mov_b32 m0, s76
	s_nop 0
	global_load_lds_dwordx4 v[236:237], off
	s_waitcnt vmcnt(8)
	s_waitcnt lgkmcnt(0)
	s_barrier
	s_setprio 1
	s_waitcnt lgkmcnt(0)
	v_mfma_f32_16x16x32_bf16 v[126:129], v[142:145], v[174:177], v[126:129]
	v_mfma_f32_16x16x32_bf16 v[126:129], v[146:149], v[178:181], v[126:129]
	v_mfma_f32_16x16x32_bf16 v[122:125], v[150:153], v[174:177], v[122:125]
	v_mfma_f32_16x16x32_bf16 v[122:125], v[154:157], v[178:181], v[122:125]
	v_mfma_f32_16x16x32_bf16 v[118:121], v[142:145], v[182:185], v[118:121]
	v_mfma_f32_16x16x32_bf16 v[118:121], v[146:149], v[186:189], v[118:121]
	v_mfma_f32_16x16x32_bf16 v[114:117], v[150:153], v[182:185], v[114:117]
	v_mfma_f32_16x16x32_bf16 v[114:117], v[154:157], v[186:189], v[114:117]
	v_mfma_f32_16x16x32_bf16 v[102:105], v[142:145], v[190:193], v[102:105]
	v_mfma_f32_16x16x32_bf16 v[102:105], v[146:149], v[210:213], v[102:105]
	v_mfma_f32_16x16x32_bf16 v[98:101], v[150:153], v[190:193], v[98:101]
	v_mfma_f32_16x16x32_bf16 v[98:101], v[154:157], v[210:213], v[98:101]
	v_mfma_f32_16x16x32_bf16 v[86:89], v[142:145], v[228:231], v[86:89]
	v_mfma_f32_16x16x32_bf16 v[86:89], v[146:149], v[232:235], v[86:89]
	v_mfma_f32_16x16x32_bf16 v[82:85], v[150:153], v[228:231], v[82:85]
	v_mfma_f32_16x16x32_bf16 v[82:85], v[154:157], v[232:235], v[82:85]
	s_setprio 0
	s_setprio 1
	v_mfma_f32_16x16x32_bf16 v[110:113], v[158:161], v[174:177], v[110:113]
	v_mfma_f32_16x16x32_bf16 v[110:113], v[162:165], v[178:181], v[110:113]
	v_mfma_f32_16x16x32_bf16 v[106:109], v[166:169], v[174:177], v[106:109]
	v_mfma_f32_16x16x32_bf16 v[106:109], v[170:173], v[178:181], v[106:109]
	v_mfma_f32_16x16x32_bf16 v[94:97], v[158:161], v[182:185], v[94:97]
	v_mfma_f32_16x16x32_bf16 v[94:97], v[162:165], v[186:189], v[94:97]
	v_mfma_f32_16x16x32_bf16 v[90:93], v[166:169], v[182:185], v[90:93]
	v_mfma_f32_16x16x32_bf16 v[90:93], v[170:173], v[186:189], v[90:93]
	v_mfma_f32_16x16x32_bf16 v[78:81], v[158:161], v[190:193], v[78:81]
	v_mfma_f32_16x16x32_bf16 v[78:81], v[162:165], v[210:213], v[78:81]
	v_mfma_f32_16x16x32_bf16 v[74:77], v[166:169], v[190:193], v[74:77]
	v_mfma_f32_16x16x32_bf16 v[74:77], v[170:173], v[210:213], v[74:77]
	v_mfma_f32_16x16x32_bf16 v[70:73], v[158:161], v[228:231], v[70:73]
	v_mfma_f32_16x16x32_bf16 v[70:73], v[162:165], v[232:235], v[70:73]
	v_mfma_f32_16x16x32_bf16 v[66:69], v[166:169], v[228:231], v[66:69]
	v_mfma_f32_16x16x32_bf16 v[66:69], v[170:173], v[232:235], v[66:69]
	s_setprio 0
	s_barrier
; #define PG8_STAGE(bufoff, gbase, voff) do { _Pragma("unroll") for (int _i = 0; _i < 2; ++_i) \
;         __builtin_amdgcn_global_load_lds((const unsigned*)((const char*)(gbase) + (voff)[_i]), (PG8_LAS unsigned*)(lds + (bufoff) + ldsw + _i * 8192), 16, 0, 0); } while (0)
; #define PG8_LDA(dst, b, h) do { _Pragma("unroll") for (int m = 0; m < 4; ++m) _Pragma("unroll") for (int k = 0; k < 2; ++k) dst[m][k] = *(const PG8_LAS bf16x8*)(lds + PG8_SA(b, h) + aoff + m * 2048 + k * 1024); } while (0)
; #define PG8_MMA(ai, bj, At, Bt) do { __builtin_amdgcn_s_setprio(1); _Pragma("unroll") for (int m = 0; m < 4; ++m) _Pragma("unroll") for (int n = 0; n < 2; ++n) _Pragma("unroll") for (int k = 0; k < 2; ++k) \
;         acc[ai][bj][m][n] = __builtin_amdgcn_mfma_f32_16x16x32_bf16(Bt[n][k], At[m][k], acc[ai][bj][m][n], 0, 0, 0); __builtin_amdgcn_s_setprio(0); } while (0)
; #define PG8_WAIT_V(n) asm volatile("s_waitcnt vmcnt(" #n ")" ::: "memory")
; #define PG8_WAIT_L(n) asm volatile("s_waitcnt lgkmcnt(" #n ")" ::: "memory")
; #define PG8_BAR __builtin_amdgcn_s_barrier()
; #define PG8_SCHED __builtin_amdgcn_sched_barrier(0)
; template <class Epi, class Sched, bool ALIGN_EPI = false, bool SP2 = false>
; __device__ __forceinline__ void gemm_phase(PG8_LAS unsigned char* lds, const Gemm g, const Sched& S, const Epi& E) {
;     ...
;             PG8_LDA(At, 1, 1); PG8_STAGE(PG8_SB(1, 0), b3, voffB); PG8_STAGE(PG8_SB(1, 1), b3 + hstepB, voffB); PG8_STAGE(PG8_SA(1, 0), a3, voffA);
;             PG8_WAIT_V(8); PG8_WAIT_L(0); PG8_BAR; PG8_MMA(1, 0, At, B0); PG8_MMA(1, 1, At, B1); PG8_BAR; PG8_SCHED;
	s_mov_b32 m0, vcc_lo
	v_lshl_add_u64 v[194:195], v[194:195], 0, s[94:95]
	ds_read_b128 v[174:177], v140 offset:49152
	ds_read_b128 v[178:181], v140 offset:50176
	ds_read_b128 v[182:185], v140 offset:51200
	ds_read_b128 v[186:189], v140 offset:52224
	ds_read_b128 v[190:193], v140 offset:53248
	ds_read_b128 v[210:213], v140 offset:54272
	ds_read_b128 v[228:231], v140 offset:55296
	ds_read_b128 v[232:235], v140 offset:56320
	global_load_lds_dwordx4 v[194:195], off
	v_lshl_add_u64 v[194:195], v[214:215], 0, s[94:95]
	s_mov_b32 m0, s86
	s_nop 0
	global_load_lds_dwordx4 v[194:195], off
	v_lshl_add_u64 v[194:195], s[42:43], 0, v[0:1]
	s_mov_b32 m0, s33
	s_nop 0
	global_load_lds_dwordx4 v[194:195], off
	v_lshl_add_u64 v[194:195], s[42:43], 0, v[132:133]
	s_mov_b32 m0, s68
	s_nop 0
	global_load_lds_dwordx4 v[194:195], off
	v_lshl_add_u64 v[194:195], v[222:223], 0, s[94:95]
	s_mov_b32 m0, s77
	s_nop 0
	global_load_lds_dwordx4 v[194:195], off
	v_lshl_add_u64 v[194:195], v[224:225], 0, s[94:95]
	s_mov_b32 m0, s83
	s_nop 0
	global_load_lds_dwordx4 v[194:195], off
	s_waitcnt vmcnt(8)
	s_waitcnt lgkmcnt(0)
	s_barrier
	s_setprio 1
	s_waitcnt lgkmcnt(0)
	v_mfma_f32_16x16x32_bf16 v[62:65], v[142:145], v[174:177], v[62:65]
	v_mfma_f32_16x16x32_bf16 v[62:65], v[146:149], v[178:181], v[62:65]
	v_mfma_f32_16x16x32_bf16 v[58:61], v[150:153], v[174:177], v[58:61]
	v_mfma_f32_16x16x32_bf16 v[58:61], v[154:157], v[178:181], v[58:61]
	v_mfma_f32_16x16x32_bf16 v[54:57], v[142:145], v[182:185], v[54:57]
	v_mfma_f32_16x16x32_bf16 v[54:57], v[146:149], v[186:189], v[54:57]
	v_mfma_f32_16x16x32_bf16 v[50:53], v[150:153], v[182:185], v[50:53]
	v_mfma_f32_16x16x32_bf16 v[50:53], v[154:157], v[186:189], v[50:53]
	v_mfma_f32_16x16x32_bf16 v[38:41], v[142:145], v[190:193], v[38:41]
	v_mfma_f32_16x16x32_bf16 v[38:41], v[146:149], v[210:213], v[38:41]
	v_mfma_f32_16x16x32_bf16 v[34:37], v[150:153], v[190:193], v[34:37]
	v_mfma_f32_16x16x32_bf16 v[34:37], v[154:157], v[210:213], v[34:37]
	v_mfma_f32_16x16x32_bf16 v[22:25], v[142:145], v[228:231], v[22:25]
	v_mfma_f32_16x16x32_bf16 v[22:25], v[146:149], v[232:235], v[22:25]
	v_mfma_f32_16x16x32_bf16 v[18:21], v[150:153], v[228:231], v[18:21]
	v_mfma_f32_16x16x32_bf16 v[18:21], v[154:157], v[232:235], v[18:21]
	s_setprio 0
	s_setprio 1
	v_mfma_f32_16x16x32_bf16 v[46:49], v[158:161], v[174:177], v[46:49]
	v_mfma_f32_16x16x32_bf16 v[46:49], v[162:165], v[178:181], v[46:49]
	v_mfma_f32_16x16x32_bf16 v[42:45], v[166:169], v[174:177], v[42:45]
	v_mfma_f32_16x16x32_bf16 v[42:45], v[170:173], v[178:181], v[42:45]
	v_mfma_f32_16x16x32_bf16 v[30:33], v[158:161], v[182:185], v[30:33]
	v_mfma_f32_16x16x32_bf16 v[30:33], v[162:165], v[186:189], v[30:33]
	v_mfma_f32_16x16x32_bf16 v[26:29], v[166:169], v[182:185], v[26:29]
	v_mfma_f32_16x16x32_bf16 v[26:29], v[170:173], v[186:189], v[26:29]
	v_mfma_f32_16x16x32_bf16 v[14:17], v[158:161], v[190:193], v[14:17]
	v_mfma_f32_16x16x32_bf16 v[14:17], v[162:165], v[210:213], v[14:17]
	v_mfma_f32_16x16x32_bf16 v[10:13], v[166:169], v[190:193], v[10:13]
	v_mfma_f32_16x16x32_bf16 v[10:13], v[170:173], v[210:213], v[10:13]
	v_mfma_f32_16x16x32_bf16 v[6:9], v[158:161], v[228:231], v[6:9]
	v_mfma_f32_16x16x32_bf16 v[6:9], v[162:165], v[232:235], v[6:9]
	v_mfma_f32_16x16x32_bf16 v[2:5], v[166:169], v[228:231], v[2:5]
	v_mfma_f32_16x16x32_bf16 v[2:5], v[170:173], v[232:235], v[2:5]
	s_setprio 0
	s_barrier
	s_movk_i32 s44, 0x100
	s_andn2_b64 vcc, exec, s[6:7]
	s_mov_b64 s[42:43], -1
	s_mov_b64 s[6:7], 0
	s_cbranch_vccz .LBB0_1403
	s_and_b64 vcc, exec, s[12:13]
	s_mov_b32 s91, 0x6c000
	s_cbranch_vccz .LBB0_1406
	s_barrier
